# MLA kv up-projection GEMM runs 2 K-tiles per unit instead of 4 (upper half of K is zero padding)
# speedup vs baseline: 1.0112x; 1.0014x over previous
;     __device__ __forceinline__ bool next(int i, pg8::Unit& u) const {
;         const int L = i * G + c;
;         if (L < n_lat) {
;             const int wgid = (L & 7) * (n_lat >> 3) + (L >> 3), nig = 8 * nN, w = wgid % nig;
;             u.pm = (((wgid / nig) ^ (ksplit >> 8)) * 8 + (w & 7)) | (ntfull << 16); u.pn = w >> 3; return true; }
;         const int q = L - n_lat; if (q >= n_ctx) return false;
;         const int ksp = ksplit & 0xff, ks = q % ksp, rest = q / ksp; u.pn = (rest % nN) | (ks << 16) | (ksp > 1 ? (1 << 30) : 0); u.pm = (128 + rest / nN) | ((ntfull / ksp) << 16); return true;
; __global__ void __launch_bounds__(NTHR) fwd_megakernel(Args a_unused) {
;     ...
;                     if (j == 4) { A = XN; Bt = (const bf16_t*)(wb + W_IN); O = (bf16_t*)(ws + OFF_Z); N = 2048; K = D; ldc = INW; }
;                     else if (q == 0) { A = (const bf16_t*)(ws + OFF_CQN); Bt = (const bf16_t*)(wb + W_UQ); O = (bf16_t*)(ws + OFF_QRAW); N = 768; K = 256; ldc = 576; }
;                     else { A = (const bf16_t*)(ws + OFF_CKVN); Bt = (const bf16_t*)(wb + W_UKV); O = (bf16_t*)(ws + OFF_KVRAW); N = 768; K = 256; ldc = 768; }
;                     pg8::Gemm g{A, Bt, MTOT, N, K}; CtxOrder S; S.init(N, K, G, bid, 4, 1);
.LBB0_958:
	s_andn2_b64 vcc, exec, s[0:1]
	v_mbcnt_lo_u32_b32 v16, -1, 0
	v_mbcnt_hi_u32_b32 v16, -1, v16
	s_cbranch_vccnz .LBB0_960
	s_and_b64 s[20:21], s[14:15], exec
	s_movk_i32 s16, 0x240
	s_cselect_b32 s53, s16, 0x300
	s_mov_b32 s16, 0x11cd0000
	s_cselect_b32 s16, s16, 0x141f0000
	s_add_u32 s20, s10, s16
	s_addc_u32 s21, s11, 0
	s_and_b64 s[26:27], s[14:15], exec
	s_mov_b32 s16, 0x3900000
	s_cselect_b32 s16, s16, 0x3960000
	s_add_u32 s26, s10, s16
	s_addc_u32 s27, s11, 0
	s_and_b64 s[28:29], s[14:15], exec
	s_cselect_b32 s16, 0xfbd0000, s73
	s_add_u32 s28, s10, s16
	s_addc_u32 s29, s11, 0
	s_mov_b32 s54, 3
	s_movk_i32 s44, 0x100
	s_cmp_lg_u64 s[14:15], 0
	s_cselect_b32 s92, 0, 1
	s_branch .LBB0_961
.LBB0_960:
	s_mov_b32 s54, 8
	s_movk_i32 s44, 0x400
	s_mov_b32 s92, 0
	s_movk_i32 s53, 0x7a0
	s_mov_b64 s[20:21], s[12:13]
	s_mov_b64 s[26:27], s[2:3]
	s_mov_b64 s[28:29], s[74:75]
.LBB0_961:
	v_add_u32_e32 v1, s50, v16
	s_lshl_b32 s55, s54, 7
	s_lshl_b32 s56, s54, 2
	v_readfirstlane_b32 s42, v1
	s_cmp_ge_i32 s89, s55
	s_mov_b64 s[34:35], -1
	s_cbranch_scc0 .LBB0_964
	s_sub_i32 s16, s89, s55
	s_mov_b64 s[34:35], 0
	s_cmp_ge_i32 s16, s56
	s_mov_b64 s[38:39], 0
	s_cbranch_scc1 .LBB0_964
	s_sext_i32_i16 s38, s16
	v_cvt_f32_ubyte0_e32 v3, s54
	v_cvt_f32_i32_e32 v2, s38
	v_rcp_iflag_f32_e32 v4, v3
	s_ashr_i32 s38, s38, 30
	s_lshl_b32 s40, s44, 10
	s_lshr_b32 s40, s40, s92
	s_or_b32 s41, s38, 1
	v_mul_f32_e32 v4, v2, v4
	v_trunc_f32_e32 v4, v4
	v_fma_f32 v2, -v4, v3, v2
	v_cvt_i32_f32_e32 v4, v4
	v_cmp_ge_f32_e64 s[38:39], |v2|, v3
	s_and_b64 s[38:39], s[38:39], exec
	s_cselect_b32 s38, s41, 0
	v_readfirstlane_b32 s39, v4
	s_add_i32 s38, s39, s38
	s_sext_i32_i16 s39, s38
	s_mul_i32 s38, s38, s54
	s_sub_i32 s16, s16, s38
	s_addk_i32 s39, 0x80
	s_sext_i32_i16 s67, s16
	s_or_b32 s68, s39, s40
	s_mov_b64 s[38:39], -1
.LBB0_964:
	s_andn2_b64 vcc, exec, s[34:35]
	s_cbranch_vccnz .LBB0_966
	s_lshl_b32 s16, s54, 3
	v_cvt_f32_ubyte0_e32 v2, s16
	v_rcp_iflag_f32_e32 v2, v2
	s_sub_i32 s35, 0, s16
	s_mul_i32 s34, s51, s54
	s_add_i32 s34, s34, s52
	v_mul_f32_e32 v2, 0x4f7ffffe, v2
	v_cvt_u32_f32_e32 v2, v2
	s_abs_i32 s39, s34
	s_ashr_i32 s38, s34, 31
	v_readfirstlane_b32 s40, v2
	s_mul_i32 s35, s35, s40
	s_mul_hi_u32 s35, s40, s35
	s_add_i32 s40, s40, s35
	s_mul_hi_u32 s35, s39, s40
	s_mul_i32 s40, s35, s16
	s_sub_i32 s39, s39, s40
	s_add_i32 s41, s35, 1
	s_sub_i32 s40, s39, s16
	s_cmp_ge_u32 s39, s16
	s_cselect_b32 s35, s41, s35
	s_cselect_b32 s39, s40, s39
	s_add_i32 s40, s35, 1
	s_cmp_ge_u32 s39, s16
	s_cselect_b32 s35, s40, s35
	s_xor_b32 s35, s35, s38
	s_sub_i32 s35, s35, s38
	s_mul_i32 s16, s35, s16
	s_sub_i32 s16, s34, s16
	s_lshl_b32 s34, s35, 3
	s_and_b32 s35, s16, 7
	s_or_b32 s34, s34, s35
	s_lshl_b32 s35, s44, 10
	s_lshr_b32 s35, s35, s92
	s_or_b32 s68, s34, s35
	s_ashr_i32 s67, s16, 3
	s_mov_b64 s[38:39], -1

; #define PG8_STAGE(bufoff, gbase, voff) do { _Pragma("unroll") for (int _i = 0; _i < 2; ++_i) \
;         __builtin_amdgcn_global_load_lds((const unsigned*)((const char*)(gbase) + (voff)[_i]), (PG8_LAS unsigned*)(lds + (bufoff) + ldsw + _i * 8192), 16, 0, 0); } while (0)
; #define PG8_WAIT_V(n) asm volatile("s_waitcnt vmcnt(" #n ")" ::: "memory")
; #define PG8_BAR __builtin_amdgcn_s_barrier()
; template <class Epi, class Sched, bool ALIGN_EPI = false, bool SP2 = false>
; __device__ __forceinline__ void gemm_phase(PG8_LAS unsigned char* lds, const Gemm g, const Sched& S, const Epi& E, const int tid_in) {
;     ...
;         PG8_STAGE(PG8_SB(1, 0), cB + kstep, voffB); PG8_STAGE(PG8_SA(1, 0), cA + kstep, voffA); PG8_STAGE(PG8_SB(1, 1), cB + hstep + kstep, voffB);
;         PG8_WAIT_V(6); PG8_BAR;
.LBB0_969:
	s_add_i32 m0, s59, 0x18000
	v_lshl_add_u64 v[2:3], v[2:3], 0, s[24:25]
	s_waitcnt vmcnt(2)
	s_barrier
	global_load_lds_dwordx4 v[2:3], off
	v_lshl_add_u64 v[2:3], v[4:5], 0, s[24:25]
	s_add_i32 m0, s59, 0x1a000
	s_add_i32 s65, s59, 0x8000
	global_load_lds_dwordx4 v[2:3], off
	v_lshl_add_u64 v[2:3], v[10:11], 0, s[24:25]
	s_mov_b32 m0, s65
	s_add_i32 s66, s59, 0xa000
	global_load_lds_dwordx4 v[2:3], off
	v_lshl_add_u64 v[2:3], v[12:13], 0, s[24:25]
	s_mov_b32 m0, s66
	v_bfe_u32 v146, v16, 4, 2
	global_load_lds_dwordx4 v[2:3], off
	s_add_i32 m0, s59, 0x1c000
	v_lshl_add_u64 v[2:3], v[6:7], 0, s[24:25]
	global_load_lds_dwordx4 v[2:3], off
	v_lshl_add_u64 v[2:3], v[8:9], 0, s[24:25]
	s_add_i32 m0, s59, 0x1e000
	v_and_b32_e32 v1, 15, v16
	global_load_lds_dwordx4 v[2:3], off
	v_cvt_f32_ubyte0_e32 v2, s54
	v_rcp_iflag_f32_e32 v2, v2
	v_lshlrev_b32_e32 v21, 4, v146
	v_lshlrev_b32_e32 v16, 2, v16
	s_lshl_b32 s63, s38, 6
	v_lshl_or_b32 v21, v1, 6, v21
	s_lshl_b32 s38, s38, 13
	v_and_b32_e32 v16, 32, v16
	v_bitop3_b32 v22, v21, s38, v16 bitop3:0xde
	s_lshl_b32 s38, s39, 5
	v_mul_f32_e32 v2, 0x4f7ffffe, v2
	s_and_b32 s64, s38, 0x60
	v_cvt_u32_f32_e32 v2, v2
	s_lshl_b32 s38, s64, 7
	s_cmpk_lt_u32 s42, 0x100
	s_cselect_b64 s[42:43], -1, 0
	s_lshl_b32 s71, s54, 3
	v_readfirstlane_b32 s39, v2
	v_cvt_f32_ubyte0_e32 v2, s71
	v_rcp_iflag_f32_e32 v2, v2
	v_bitop3_b32 v147, s38, v21, v16 bitop3:0xf6
	s_sub_i32 s38, 0, s54
	s_mul_i32 s38, s38, s39
	v_mul_f32_e32 v2, 0x4f7ffffe, v2
	v_cvt_u32_f32_e32 v2, v2
	s_mul_hi_u32 s38, s39, s38
	s_add_i32 s73, s39, s38
	s_sub_i32 s38, 0, s71
	v_readfirstlane_b32 s39, v2
	v_add_u32_e32 v2, v17, v14
	v_add_lshl_u32 v2, v2, v15, 1
	v_mov_b32_e32 v3, v0
	s_waitcnt vmcnt(6)
	s_mul_i32 s38, s38, s39
	v_lshl_add_u64 v[138:139], s[16:17], 0, v[2:3]
	v_add_u32_e32 v2, v20, v18
	s_mul_hi_u32 s38, s39, s38
	v_add_lshl_u32 v2, v2, v19, 1
	s_lshl_b32 s69, s44, 10
	s_lshr_b32 s69, s69, s92
	s_lshl_b32 s70, s54, 4
	s_mov_b32 s72, 0
	s_add_i32 s76, s39, s38
	s_add_i32 s77, s53, 0xffffff80
	v_lshl_add_u64 v[140:141], s[16:17], 0, v[2:3]
	v_add_u32_e32 v148, 0, v22
	s_barrier
	s_branch .LBB0_972
